# m2a: additionally overlap the conv pass's previous-token loads with the first iteration's token loads (one fewer serialized HBM round trip per pass)
# speedup vs baseline: 1.0010x; 1.0010x over previous
; __device__ __forceinline__ float bf2f(unsigned v) { return __uint_as_float(v << 16); }
; PH_FN ph_m2a(const Params& prm, unsigned char* lds, int l_) {
;     ...
;         for (int cp = C.tid; cp < 768; cp += NTHREADS) {
;             const int c = 2 * cp;
;             const f32x2 w0 = *(const f32x2*)(conv_w + c), w1 = *(const f32x2*)(conv_w + 1536 + c), w2 = *(const f32x2*)(conv_w + 3072 + c), w3 = *(const f32x2*)(conv_w + 4608 + c), cb = *(const f32x2*)(conv_b + c);
;             f32x2 xm3 = {0.f, 0.f}, xm2 = {0.f, 0.f}, xm1 = {0.f, 0.f};
;             const bf16_t* __restrict__ src = PROJ + (size_t)tb * LDP + XBC0 + c;
;             if (sl0 > 0) { unsigned u;
;                 u = *(const unsigned*)(src - 3 * (size_t)LDP); xm3 = (f32x2){bf2f(u & 0xffffu), bf2f(u >> 16)};
;                 u = *(const unsigned*)(src - 2 * (size_t)LDP); xm2 = (f32x2){bf2f(u & 0xffffu), bf2f(u >> 16)};
;                 u = *(const unsigned*)(src - 1 * (size_t)LDP); xm1 = (f32x2){bf2f(u & 0xffffu), bf2f(u >> 16)}; }
;             const int h = (c >> 6) & 15;
;             const bool isx = c < 1024, isb = (c >= 1024 && c < 1280);
;             const int rr = isx ? 64 : 128, r0 = isx ? ((c & 63) >> 1) : (((c - 1024) & 127) >> 1);
;             bf16_t* __restrict__ d0 = (isx ? XT + (size_t)(b * 16 + h) * 64 * SEQ : BTS + (size_t)(b * 2 + ((c - 1024) >> 7)) * 128 * SEQ) + ((size_t)(sl0 >> 3) * rr + r0) * 8;
.LBB0_301:
	v_lshlrev_b32_e32 v2, 1, v69
	v_ashrrev_i32_e32 v3, 31, v2
	v_lshlrev_b64 v[4:5], 2, v[2:3]
	v_lshl_add_u64 v[6:7], s[0:1], 0, v[4:5]
	v_lshl_add_u64 v[8:9], s[2:3], 0, v[4:5]
	v_lshl_add_u64 v[14:15], s[78:79], 0, v[4:5]
	v_lshl_add_u64 v[16:17], s[80:81], 0, v[4:5]
	global_load_dwordx2 v[26:27], v[6:7], off
	global_load_dwordx2 v[28:29], v[8:9], off
	global_load_dwordx2 v[30:31], v[14:15], off
	global_load_dwordx2 v[32:33], v[16:17], off
	v_lshl_add_u64 v[4:5], s[34:35], 0, v[4:5]
	global_load_dwordx2 v[34:35], v[4:5], off
	s_andn2_b64 vcc, exec, s[66:67]
	s_cbranch_vccnz .LBB0_303
	v_lshl_add_u64 v[4:5], v[2:3], 1, s[62:63]
	v_add_co_u32_e32 v6, vcc, 0xffff5000, v4
	s_nop 1
	v_addc_co_u32_e32 v7, vcc, -1, v5, vcc
	v_add_co_u32_e32 v8, vcc, 0xffff9000, v4
	s_nop 1
	v_addc_co_u32_e32 v9, vcc, -1, v5, vcc
	v_add_co_u32_e32 v4, vcc, 0xffffd000, v4
	global_load_dword v104, v[6:7], off offset:-2048
	s_nop 0
	global_load_dword v105, v[8:9], off offset:-2048
	v_addc_co_u32_e32 v5, vcc, -1, v5, vcc
	global_load_dword v106, v[4:5], off offset:-2048
	s_branch .LBB0_304
.LBB0_303:
	v_mov_b32_e32 v104, v1
	v_mov_b32_e32 v105, v1
	v_mov_b32_e32 v106, v1
.LBB0_304:
	v_cmp_gt_i32_e32 vcc, s41, v69
	v_cmp_lt_i32_e64 s[22:23], s36, v69
	s_and_saveexec_b64 s[8:9], s[22:23]
	s_xor_b64 s[8:9], exec, s[8:9]
	v_add_u32_e32 v0, 0xfffffc00, v2
	v_lshrrev_b32_e32 v0, 7, v0
	v_add_u32_e32 v4, s5, v0
	s_or_saveexec_b64 s[8:9], s[8:9]
	v_mov_b64_e32 v[8:9], 7
	v_mov_b32_e32 v70, 7
	v_mov_b64_e32 v[6:7], 0x200
	v_mov_b64_e32 v[14:15], 0x8964000
	v_mov_b64_e32 v[16:17], 20
	s_xor_b64 exec, exec, s[8:9]
	v_lshrrev_b32_e32 v0, 5, v69
	v_and_or_b32 v4, v0, 15, s93
	v_mov_b64_e32 v[8:9], 6
	v_mov_b32_e32 v70, 6
	v_mov_b64_e32 v[6:7], 0x100
	v_mov_b64_e32 v[14:15], 0x1964000
	v_mov_b64_e32 v[16:17], 19
	s_or_b64 exec, exec, s[8:9]
	v_lshrrev_b32_e32 v5, 3, v69
	v_and_b32_e32 v5, 60, v5
	v_add_u32_e32 v71, 16, v5
	v_ashrrev_i32_e32 v5, 31, v4
	v_cndmask_b32_e64 v0, 63, 31, vcc
	v_lshl_add_u64 v[14:15], s[26:27], 0, v[14:15]
	v_lshlrev_b64 v[4:5], v16, v[4:5]
	v_lshlrev_b64 v[8:9], v8, s[64:65]
	v_ashrrev_i32_e32 v13, 31, v12
	v_lshl_add_u64 v[4:5], v[14:15], 0, v[4:5]
	v_and_or_b32 v8, v0, v69, v8
	v_lshlrev_b64 v[2:3], 1, v[2:3]
	s_movk_i32 s8, 0x280
	v_lshl_add_u64 v[36:37], v[12:13], 1, s[84:85]
	v_lshl_add_u64 v[38:39], v[8:9], 4, v[4:5]
	v_lshl_add_u64 v[40:41], s[76:77], 0, v[2:3]
	v_lshl_add_u64 v[42:43], s[26:27], 0, v[2:3]
	v_cmp_gt_i32_e64 s[24:25], s8, v69
	s_mov_b32 s53, 0
	s_mov_b64 s[30:31], 0
	v_lshlrev_b32_e32 v14, 1, v6
	s_mov_b32 s56, s4
	v_lshl_add_u64 v[44:45], v[36:37], 0, s[30:31]
	v_add_co_u32_e32 v74, vcc, 0x9964000, v44
	s_nop 1
	v_addc_co_u32_e32 v75, vcc, 0, v45, vcc
	global_load_dword v80, v[74:75], off offset:2048
	v_add_co_u32_e32 v74, vcc, 0x9968000, v44
	s_nop 1
	v_addc_co_u32_e32 v75, vcc, 0, v45, vcc
	global_load_dword v81, v[74:75], off offset:2048
	v_add_co_u32_e32 v74, vcc, 0x996c000, v44
	s_nop 1
	v_addc_co_u32_e32 v75, vcc, 0, v45, vcc
	global_load_dword v82, v[74:75], off offset:2048
	v_add_co_u32_e32 v74, vcc, 0x9970000, v44
	s_nop 1
	v_addc_co_u32_e32 v75, vcc, 0, v45, vcc
	global_load_dword v83, v[74:75], off offset:2048
	v_add_co_u32_e32 v74, vcc, 0x9974000, v44
	s_nop 1
	v_addc_co_u32_e32 v75, vcc, 0, v45, vcc
	global_load_dword v84, v[74:75], off offset:2048
	v_add_co_u32_e32 v74, vcc, 0x9978000, v44
	s_nop 1
	v_addc_co_u32_e32 v75, vcc, 0, v45, vcc
	global_load_dword v85, v[74:75], off offset:2048
	v_add_co_u32_e32 v74, vcc, 0x997c000, v44
	s_nop 1
	v_addc_co_u32_e32 v75, vcc, 0, v45, vcc
	global_load_dword v86, v[74:75], off offset:2048
	v_add_co_u32_e32 v74, vcc, 0x9980000, v44
	s_nop 1
	v_addc_co_u32_e32 v75, vcc, 0, v45, vcc
	global_load_dword v87, v[74:75], off offset:2048
	s_waitcnt vmcnt(8)
	v_lshlrev_b32_e32 v50, 16, v104
	v_and_b32_e32 v51, 0xffff0000, v104
	v_lshlrev_b32_e32 v48, 16, v105
	v_and_b32_e32 v49, 0xffff0000, v105
	v_lshlrev_b32_e32 v52, 16, v106
	v_and_b32_e32 v53, 0xffff0000, v106
	s_branch .LBB0_310
